# stack5 + PE elementwise phase: rows owned per XCD (blockIdx % 8) matching the GEMMs' m-tile ownership, swept from the last-written stripe downwards (L2 locality)
# baseline (speedup 1.0000x reference)
; #define KA() ([]() __attribute__((always_inline)) { KArgs p_ = (KArgs)__builtin_amdgcn_kernarg_segment_ptr(); asm volatile("" : "+s"(p_)); return p_; }())
; #define PH_IDS() int tid = TID_NOW(); asm volatile("" : "+v"(tid)); const int lane = tid & 63, wave = __builtin_amdgcn_readfirstlane(tid >> 6); int bx = blockIdx.x; asm volatile("" : "+s"(bx)); \
;     const int G = gridDim.x, vcu = (G % 8 == 0) ? (bx % 8) * (G / 8) + bx / 8 : bx, gw = vcu * NWAVES + wave, NGW = G * NWAVES; (void)lane; (void)gw; (void)NGW; (void)vcu
; __global__ void __launch_bounds__(NWAVES * 64, 2) hymba_fwd(Args args_unused) {
;     ...
;             KArgs A = KA(); PH_IDS(); const bf16* Y1 = (const bf16*)(A->ws + WS_Y1); bf16* XB = (bf16*)(A->ws + WS_XN); float* RS2 = (float*)(A->ws + WS_RS2); const float* x_in = IN_F(A, 0);
;             f32x4 gp[4]; load_row(IN_F(A, 11) + l * D, lane, gp);
;             f32x4 y[4], xv[4];
;             load_row_bf16_nt(Y1 + (size_t)gw * D, lane, y); if (l == 0) load_row_nt(x_in + (size_t)gw * D, lane, xv); else load_row_bf16(XB + (size_t)gw * D, lane, xv);
;             for (int m = gw; m < M; m += NGW) { f32x4 yn[4], xn[4];
;                 const int mn = (m + NGW < M) ? m + NGW : m;
;                 load_row_bf16_nt(Y1 + (size_t)mn * D, lane, yn); if (l == 0) load_row_nt(x_in + (size_t)mn * D, lane, xn); else load_row_bf16(XB + (size_t)mn * D, lane, xn);
.LBB0_547:
	s_load_dwordx2 s[12:13], s[14:15], 0x90
	s_load_dwordx2 s[2:3], s[14:15], 0x58
	s_ashr_i32 s0, s0, 6
	s_lshl_b32 s1, s1, 3
	s_and_b32 s6, s82, 7
	s_lshl_b32 s6, s6, 12
	s_lshr_b32 s1, s82, 3
	s_lshl_b32 s1, s1, 3
	s_add_i32 s6, s6, s1
	s_add_i32 s6, s6, s0
	s_addk_i32 s6, 0xf00
	s_mov_b32 s0, s6
	s_mov_b32 s1, 0
	s_waitcnt lgkmcnt(0)
	s_add_u32 s4, s12, 0x7800000
	s_addc_u32 s5, s13, 0
	s_add_u32 s10, s12, 0x3800000
	s_addc_u32 s11, s13, 0
	s_lshl_b32 s38, s26, 10
	s_lshl_b64 s[8:9], s[38:39], 2
	v_and_b32_e32 v28, 63, v0
	s_add_u32 s2, s2, s8
	s_addc_u32 s3, s3, s9
	v_lshlrev_b32_e32 v18, 4, v28
	s_ashr_i32 s7, s6, 31
	s_load_dwordx2 s[14:15], s[14:15], 0x0
	global_load_dwordx4 v[34:37], v18, s[2:3]
	global_load_dwordx4 v[38:41], v18, s[2:3] offset:1024
	global_load_dwordx4 v[42:45], v18, s[2:3] offset:2048
	global_load_dwordx4 v[46:49], v18, s[2:3] offset:3072
	s_lshl_b64 s[16:17], s[6:7], 10
	s_lshl_b64 s[2:3], s[6:7], 11
	s_add_u32 s2, s4, s2
	s_addc_u32 s3, s5, s3
	v_lshlrev_b32_e32 v0, 3, v28
	global_load_dwordx2 v[26:27], v0, s[2:3] nt
	global_load_dwordx2 v[24:25], v0, s[2:3] offset:512 nt
	global_load_dwordx2 v[22:23], v0, s[2:3] offset:1024 nt
	global_load_dwordx2 v[20:21], v0, s[2:3] offset:1536 nt
	s_mov_b64 s[18:19], -1
	s_and_b64 vcc, exec, s[66:67]
	s_cbranch_vccnz .LBB0_550
	s_andn2_b64 vcc, exec, s[18:19]
	s_cbranch_vccz .LBB0_551

; __global__ void __launch_bounds__(NWAVES * 64, 2) hymba_fwd(Args args_unused) {
;     ...
;             for (int m = gw; m < M; m += NGW) { f32x4 yn[4], xn[4];
;                 const int mn = (m + NGW < M) ? m + NGW : m;
;                 load_row_bf16_nt(Y1 + (size_t)mn * D, lane, yn); if (l == 0) load_row_nt(x_in + (size_t)mn * D, lane, xn); else load_row_bf16(XB + (size_t)mn * D, lane, xn);
;                 const float ry = row_rstd(y);
; #pragma unroll
;                 for (int j = 0; j < 4; ++j) xv[j] += y[j] * ry * gp[j];
;                 store_row_bf16(XB + (size_t)m * D, lane, xv);
;                 const float rx = row_rstd(xv);
;                 if (lane == 0) RS2[m] = rx;
; #pragma unroll
;                 for (int j = 0; j < 4; ++j) { y[j] = yn[j]; xv[j] = xn[j]; }
;             }
.LBB0_553:
	s_or_b64 exec, exec, s[14:15]
	s_add_u32 s10, s10, 0xfffffc00
	s_waitcnt vmcnt(4)
	v_mov_b64_e32 v[2:3], v[18:19]
	v_lshlrev_b32_e32 v70, 16, v80
	v_and_b32_e32 v71, 0xffff0000, v80
	v_lshlrev_b32_e32 v72, 16, v81
	v_and_b32_e32 v73, 0xffff0000, v81
	v_lshlrev_b32_e32 v66, 16, v78
	v_and_b32_e32 v67, 0xffff0000, v78
	v_lshlrev_b32_e32 v68, 16, v79
	v_and_b32_e32 v69, 0xffff0000, v79
	v_lshlrev_b32_e32 v62, 16, v76
	v_and_b32_e32 v63, 0xffff0000, v76
	v_lshlrev_b32_e32 v64, 16, v77
	v_and_b32_e32 v65, 0xffff0000, v77
	v_lshlrev_b32_e32 v58, 16, v74
	v_and_b32_e32 v59, 0xffff0000, v74
	v_lshlrev_b32_e32 v60, 16, v75
	v_and_b32_e32 v61, 0xffff0000, v75
	s_addc_u32 s11, s11, -1
	s_mov_b32 s2, 0xfff80000
	s_mov_b32 s3, -1
	v_lshl_add_u64 v[56:57], v[56:57], 0, s[2:3]
	s_and_b64 vcc, exec, s[12:13]
	v_mov_b64_e32 v[4:5], v[20:21]
	v_mov_b64_e32 v[6:7], v[22:23]
	v_mov_b64_e32 v[8:9], v[24:25]
	v_mov_b64_e32 v[10:11], v[26:27]
	v_mov_b64_e32 v[12:13], v[28:29]
	v_mov_b64_e32 v[14:15], v[30:31]
	v_mov_b64_e32 v[16:17], v[32:33]
	s_cbranch_vccnz .LBB0_560
.LBB0_554:
	s_mov_b32 s0, s6
	s_addk_i32 s6, 0xff00
	s_and_b32 s1, s6, 0xfff
	s_cmpk_gt_u32 s1, 0xeff
	s_cselect_b64 s[12:13], -1, 0
	s_cselect_b32 s0, s0, s6
	s_ashr_i32 s1, s0, 31
	s_lshl_b64 s[2:3], s[0:1], 11
	v_lshl_add_u64 v[18:19], v[50:51], 0, s[2:3]
	global_load_dwordx2 v[80:81], v[18:19], off nt
	global_load_dwordx2 v[78:79], v[18:19], off offset:512 nt
	global_load_dwordx2 v[76:77], v[18:19], off offset:1024 nt
	global_load_dwordx2 v[74:75], v[18:19], off offset:1536 nt
	s_lshl_b64 s[14:15], s[0:1], 10
	s_mov_b64 s[16:17], -1
	s_and_b64 vcc, exec, s[66:67]
	s_cbranch_vccz .LBB0_556
	v_lshl_add_u64 v[18:19], s[14:15], 1, v[52:53]
	global_load_dwordx2 v[20:21], v[18:19], off
	global_load_dwordx2 v[24:25], v[18:19], off offset:512
	global_load_dwordx2 v[28:29], v[18:19], off offset:1024
	global_load_dwordx2 v[32:33], v[18:19], off offset:1536
	s_mov_b64 s[16:17], 0
	s_waitcnt vmcnt(3)
	v_lshlrev_b32_e32 v18, 16, v20
	v_and_b32_e32 v19, 0xffff0000, v20
	v_lshlrev_b32_e32 v20, 16, v21
	v_and_b32_e32 v21, 0xffff0000, v21
	s_waitcnt vmcnt(2)
	v_lshlrev_b32_e32 v22, 16, v24
	v_and_b32_e32 v23, 0xffff0000, v24
	v_lshlrev_b32_e32 v24, 16, v25
	v_and_b32_e32 v25, 0xffff0000, v25
	s_waitcnt vmcnt(1)
	v_lshlrev_b32_e32 v26, 16, v28
	v_and_b32_e32 v27, 0xffff0000, v28
	v_lshlrev_b32_e32 v28, 16, v29
	v_and_b32_e32 v29, 0xffff0000, v29
	s_waitcnt vmcnt(0)
	v_lshlrev_b32_e32 v30, 16, v32
	v_and_b32_e32 v31, 0xffff0000, v32
	v_lshlrev_b32_e32 v32, 16, v33
	v_and_b32_e32 v33, 0xffff0000, v33
